# GLA merge loop: top-of-loop vmcnt(0) (store-data WAR guard) removed so the next rows' loads overlap the store drain
# speedup vs baseline: 1.0088x; 1.0014x over previous
.LBB0_150:
	v_ashrrev_i32_e32 v63, 31, v62
	v_lshlrev_b64 v[64:65], 11, v[62:63]
	v_lshl_or_b32 v18, v42, 1, v64
	v_mov_b32_e32 v19, v65
	v_lshl_add_u64 v[20:21], s[26:27], 0, v[18:19]
	v_lshl_add_u64 v[22:23], s[94:95], 0, v[18:19]
	v_lshl_add_u64 v[18:19], s[28:29], 0, v[18:19]
	global_load_dwordx4 v[34:37], v[20:21], off
	global_load_dwordx4 v[30:33], v[20:21], off offset:16
	global_load_dwordx4 v[38:41], v[22:23], off
	global_load_dwordx4 v[26:29], v[22:23], off offset:16
	s_nop 0
	global_load_dwordx4 v[22:25], v[18:19], off
	s_nop 0
	global_load_dwordx4 v[18:21], v[18:19], off offset:16
	v_add_u32_e32 v62, s4, v62
	v_cmp_gt_i32_e32 vcc, s14, v62
	v_ashrrev_i32_e32 v63, 31, v62
	s_and_saveexec_b64 s[40:41], vcc
	s_cbranch_execz .LBB0_152
	v_lshlrev_b64 v[46:47], 11, v[62:63]
	v_lshl_or_b32 v46, v42, 1, v46
	v_lshl_add_u64 v[74:75], s[26:27], 0, v[46:47]
	v_lshl_add_u64 v[80:81], s[94:95], 0, v[46:47]
	v_lshl_add_u64 v[84:85], s[28:29], 0, v[46:47]
	global_load_dwordx4 v[56:59], v[74:75], off
	global_load_dwordx4 v[66:69], v[80:81], off
	global_load_dwordx4 v[70:73], v[84:85], off
	global_load_dwordx4 v[76:79], v[74:75], off offset:16
	s_nop 0
	global_load_dwordx4 v[80:83], v[80:81], off offset:16
	s_nop 0
	global_load_dwordx4 v[84:87], v[84:85], off offset:16
	s_waitcnt vmcnt(0) lgkmcnt(0)
	v_lshlrev_b32_e32 v46, 16, v56
	v_and_b32_e32 v47, 0xffff0000, v56
	v_lshlrev_b32_e32 v48, 16, v66
	v_and_b32_e32 v49, 0xffff0000, v66
	v_lshlrev_b32_e32 v50, 16, v57
	v_and_b32_e32 v51, 0xffff0000, v57
	v_lshlrev_b32_e32 v52, 16, v67
	v_and_b32_e32 v53, 0xffff0000, v67
	v_lshlrev_b32_e32 v54, 16, v58
	v_and_b32_e32 v55, 0xffff0000, v58
	v_lshlrev_b32_e32 v56, 16, v68
	v_and_b32_e32 v57, 0xffff0000, v68
	v_lshlrev_b32_e32 v58, 16, v59
	v_and_b32_e32 v59, 0xffff0000, v59
	v_lshlrev_b32_e32 v60, 16, v69
	v_and_b32_e32 v61, 0xffff0000, v69
	v_pk_add_f32 v[48:49], v[46:47], v[48:49]
	v_lshlrev_b32_e32 v46, 16, v70
	v_and_b32_e32 v47, 0xffff0000, v70
	v_pk_add_f32 v[52:53], v[50:51], v[52:53]
	v_lshlrev_b32_e32 v50, 16, v71
	v_and_b32_e32 v51, 0xffff0000, v71
	v_pk_add_f32 v[56:57], v[54:55], v[56:57]
	v_lshlrev_b32_e32 v54, 16, v72
	v_and_b32_e32 v55, 0xffff0000, v72
	v_pk_add_f32 v[60:61], v[58:59], v[60:61]
	v_lshlrev_b32_e32 v58, 16, v73
	v_and_b32_e32 v59, 0xffff0000, v73
	v_lshlrev_b32_e32 v66, 16, v76
	v_and_b32_e32 v67, 0xffff0000, v76
	v_lshlrev_b32_e32 v68, 16, v80
	v_and_b32_e32 v69, 0xffff0000, v80
	v_lshlrev_b32_e32 v70, 16, v77
	v_and_b32_e32 v71, 0xffff0000, v77
	v_lshlrev_b32_e32 v72, 16, v81
	v_and_b32_e32 v73, 0xffff0000, v81
	v_lshlrev_b32_e32 v74, 16, v78
	v_and_b32_e32 v75, 0xffff0000, v78
	v_lshlrev_b32_e32 v76, 16, v82
	v_and_b32_e32 v77, 0xffff0000, v82
	v_lshlrev_b32_e32 v78, 16, v79
	v_and_b32_e32 v79, 0xffff0000, v79
	v_lshlrev_b32_e32 v80, 16, v83
	v_and_b32_e32 v81, 0xffff0000, v83
	v_pk_add_f32 v[66:67], v[66:67], v[68:69]
	v_lshlrev_b32_e32 v68, 16, v84
	v_and_b32_e32 v69, 0xffff0000, v84
	v_pk_add_f32 v[70:71], v[70:71], v[72:73]
	v_lshlrev_b32_e32 v72, 16, v85
	v_and_b32_e32 v73, 0xffff0000, v85
	v_pk_add_f32 v[74:75], v[74:75], v[76:77]
	v_lshlrev_b32_e32 v76, 16, v86
	v_and_b32_e32 v77, 0xffff0000, v86
	v_pk_add_f32 v[78:79], v[78:79], v[80:81]
	v_lshlrev_b32_e32 v80, 16, v87
	v_and_b32_e32 v81, 0xffff0000, v87
